# code placement: both hand-written attention loop heads padded with s_nop 0 to 64-byte boundaries (far 0xCA80, near 0xD080)
# speedup vs baseline: 1.0105x; 1.0062x over previous
; #define AT_LOADK(t) do { AT_DMA(kg[0] + (size_t)(t) * 65536, ldsl + ((t) & 1) * AT_KS + dw); AT_DMA(kg[1] + (size_t)(t) * 65536, ldsl + ((t) & 1) * AT_KS + dw + 1024); } while (0)
; template <bool NEAR>
; DI void attn_qk(f32x16& s0, f32x16& s1, ldsp_t kb, const int* kro, const bf16x8* qf, int dtile, const float* tb2, int hi, int qg, int r32) {
;     ...
;         const int base = dtile * 64 + 8 * hi - (qg & 1) * 32 - r32 + 128;
; #pragma unroll
;         for (int k = 0; k < 16; ++k) { const int i0 = base + (k & 7) + 16 * (k >> 3), i1 = i0 + 32; s0[k] = tb2[i0 < 0 ? 0 : i0]; s1[k] = tb2[i1 < 0 ? 0 : i1]; }
; DI void attn_mfma_phase(PP P, int l, unsigned char* lds, int G, int cid) {
;     ...
;         const int w = u & 255, i = u >> 8, bh = (w & 7) * 4 + (w >> 6), r = (w >> 3) & 7, b = bh >> 3, h = bh & 7;
;         const int j = (i >> 1) * 16 + ((i & 1) ? 15 - r : r);
;         const int mychunk = 2 * j + (qg >> 1), qpos = j * 128 + qg * 32 + r32;
;         float mb = 0.f;
;         for (int k = 0; k < 32; ++k) mb = fmaxf(mb, fabsf(P->in[23][k * 8 + h]));
;         const float smax2 = (8.f * mq * mk + mb) * LOG2E;
;         __syncthreads();
;         if (tid < 192) tb2[tid] = P->in[23][t5_bucket(tid - 128) * 8 + h] * LOG2E - smax2;
;         bf16x8 qf[4];
;         { const bf16_t* qp = Zq + ((size_t)b * SEQ + qpos) * 1024 + h * 128 + map * 64 + 8 * hi;
; #pragma unroll
;           for (int ks = 0; ks < 4; ++ks) qf[ks] = *(const bf16x8*)(qp + ks * 16); }
;         f32x16 o[4];
; #pragma unroll
;         for (int et = 0; et < 4; ++et)
; #pragma unroll
;             for (int k = 0; k < 16; ++k) o[et][k] = 0.f;
;         float lsum = 0.f;
;         const bf16_t* kg[2]; const bf16_t* vg[2];
; #pragma unroll
;         for (int i2 = 0; i2 < 2; ++i2) { const int blk = wave * 2 + i2;
;             { const int row = blk * 4 + (lane >> 4), c = (lane & 15) ^ (row & 15); kg[i2] = Zk + ((size_t)b * SEQ + row) * 1024 + h * 128 + c * 8; }
;             { const int row = blk * 8 + (lane >> 3), c = (lane & 7) ^ ((row >> 1) & 7); vg[i2] = VT + ((size_t)bh * 128 + row) * SEQ + c * 8; } }
;         const int dw = wave * 2048;
;     ...
;         AT_LOADK(0); AT_LOADV(0); AT_LOADK(1);
;         __syncthreads();
;         f32x16 sc0, sc1, sn0, sn1;
;         attn_qk<true>(sc0, sc1, ldsl, kro, qf, 0 - mychunk, tb2, hi, qg, r32);
.LBB0_211:
	s_or_b64 exec, exec, s[12:13]
	s_lshr_b32 s5, s82, 6
	s_and_b32 s6, s67, -4
	s_and_b32 s5, s5, 3
	s_or_b32 s5, s6, s5
	s_lshl_b32 s4, s67, 20
	s_and_b32 s5, s5, 7
	s_bfe_u32 s6, s82, 0x30003
	s_ashr_i32 s42, s82, 5
	s_and_b32 s4, s4, 0x1800000
	s_lshl_b32 s5, s5, 8
	s_and_b32 s9, s42, -16
	s_and_b32 s10, s82, 0x100
	s_xor_b32 s11, s6, 15
	s_cmp_eq_u32 s10, 0
	s_cselect_b32 s43, s6, s11
	s_or_b32 s6, s43, s9
	s_lshl_b32 s12, s6, 7
	s_waitcnt vmcnt(30)
	v_or_b32_e32 v2, s12, v203
	s_lshl_b32 s8, s8, 9
	s_and_b32 s20, s8, 0x3000
	s_waitcnt vmcnt(29)
	v_ashrrev_i32_e32 v3, 31, v2
	v_lshl_add_u64 v[192:193], v[2:3], 0, s[20:21]
	v_lshlrev_b64 v[2:3], 11, v[192:193]
	v_lshl_add_u64 v[2:3], s[46:47], 0, v[2:3]
	s_lshl_b32 s8, s39, 8
	s_mov_b32 s9, s21
	v_lshl_add_u64 v[2:3], v[2:3], 0, s[8:9]
	v_lshl_add_u64 v[2:3], s[16:17], 1, v[2:3]
	v_lshlrev_b32_e32 v0, 1, v162
	v_lshl_add_u64 v[2:3], v[2:3], 0, v[0:1]
	global_load_dwordx4 v[156:159], v[2:3], off
	global_load_dwordx4 v[152:155], v[2:3], off offset:32
	global_load_dwordx4 v[148:151], v[2:3], off offset:64
	global_load_dwordx4 v[144:147], v[2:3], off offset:96
	s_lshl_b32 s13, s6, 1
	s_or_b32 s10, s13, s60
	s_add_u32 s8, s28, s8
	s_addc_u32 s9, s29, 0
	s_lshl_b32 s84, s7, 7
	s_mov_b32 s85, s21
	s_waitcnt vmcnt(31)
	v_lshl_add_u64 v[4:5], s[84:85], 0, v[174:175]
	v_lshl_add_u64 v[2:3], s[20:21], 0, v[172:173]
	v_lshlrev_b64 v[4:5], 13, v[4:5]
	v_lshlrev_b64 v[2:3], 11, v[2:3]
	v_lshl_add_u64 v[194:195], v[180:181], 0, v[4:5]
	v_lshl_add_u64 v[4:5], s[20:21], 0, v[176:177]
	v_lshl_add_u64 v[2:3], s[8:9], 0, v[2:3]
	v_mov_b32_e32 v189, v1
	v_lshlrev_b64 v[4:5], 11, v[4:5]
	s_mov_b32 m0, s65
	v_lshl_add_u64 v[2:3], v[2:3], 0, v[188:189]
	v_lshl_add_u64 v[4:5], s[8:9], 0, v[4:5]
	v_mov_b32_e32 v191, v1
	v_lshl_add_u64 v[4:5], v[4:5], 0, v[190:191]
	s_waitcnt vmcnt(29)
	v_lshl_add_u64 v[6:7], s[84:85], 0, v[178:179]
	global_load_lds_dwordx4 v[2:3], off
	s_add_i32 m0, s65, 0x400
	v_lshlrev_b64 v[6:7], 13, v[6:7]
	global_load_lds_dwordx4 v[4:5], off
	s_add_i32 m0, s65, 0x10000
	v_lshl_add_u64 v[196:197], v[182:183], 0, v[6:7]
	global_load_lds_dwordx4 v[194:195], off
	s_mov_b32 m0, s73
	v_lshl_add_u64 v[2:3], v[2:3], 0, s[34:35]
	global_load_lds_dwordx4 v[196:197], off
	s_add_i32 m0, s65, 0x4000
	v_lshl_or_b32 v0, s10, 6, v216
	global_load_lds_dwordx4 v[2:3], off
	v_lshl_add_u64 v[4:5], v[4:5], 0, s[34:35]
	s_mov_b32 m0, s80
	v_sub_u32_e32 v0, v162, v0
	global_load_lds_dwordx4 v[4:5], off
	s_waitcnt vmcnt(0)
	s_add_i32 m0, s65, 0x14000
	v_lshl_add_u64 v[6:7], v[194:195], 0, s[22:23]
	global_load_lds_dwordx4 v[6:7], off
	s_add_i32 m0, s65, 0x14400
	v_lshl_add_u64 v[8:9], v[196:197], 0, s[22:23]
	global_load_lds_dwordx4 v[8:9], off
	s_add_i32 m0, s65, 0x8000
	v_lshl_add_u64 v[2:3], v[2:3], 0, s[34:35]
	global_load_lds_dwordx4 v[2:3], off
	s_add_i32 m0, s65, 0x8400
	v_lshl_add_u64 v[4:5], v[4:5], 0, s[34:35]
	global_load_lds_dwordx4 v[4:5], off
	s_add_i32 m0, s65, 0x18000
	v_lshl_add_u64 v[6:7], v[6:7], 0, s[22:23]
	global_load_lds_dwordx4 v[6:7], off
	s_add_i32 m0, s65, 0x18400
	v_lshl_add_u64 v[8:9], v[8:9], 0, s[22:23]
	global_load_lds_dwordx4 v[8:9], off
	s_add_i32 m0, s65, 0xc000
	v_lshl_add_u64 v[2:3], v[2:3], 0, s[34:35]
	global_load_lds_dwordx4 v[2:3], off
	s_add_i32 m0, s65, 0xc400
	v_lshl_add_u64 v[4:5], v[4:5], 0, s[34:35]
	global_load_lds_dwordx4 v[4:5], off
	v_add_u32_e32 v10, 0x80, v0
	v_max_i32_e32 v11, 0, v10
	v_max_i32_e32 v10, 0xffffffe0, v10
	v_add_u32_e32 v12, 0x81, v0
	v_add_u32_e32 v14, 0x82, v0
	v_add_u32_e32 v16, 0x83, v0
	v_add_u32_e32 v191, 0, v171
	v_lshl_add_u32 v11, v11, 2, s61
	v_lshl_add_u32 v10, v10, 2, s61
	v_max_i32_e32 v13, 0, v12
	v_max_i32_e32 v12, 0xffffffe0, v12
	v_max_i32_e32 v15, 0, v14
	v_max_i32_e32 v14, 0xffffffe0, v14
	v_max_i32_e32 v17, 0, v16
	v_max_i32_e32 v16, 0xffffffe0, v16
	s_waitcnt lgkmcnt(0)
	s_barrier
	ds_read_b128 v[2:5], v191
	ds_read_b128 v[6:9], v191 offset:8192
	v_lshl_add_u32 v13, v13, 2, s61
	v_lshl_add_u32 v12, v12, 2, s61
	v_lshl_add_u32 v15, v15, 2, s61
	v_lshl_add_u32 v14, v14, 2, s61
	v_lshl_add_u32 v17, v17, 2, s61
	v_lshl_add_u32 v16, v16, 2, s61
	ds_read_b32 v96, v11
	ds_read_b32 v80, v10 offset:128
	ds_read_b32 v97, v13
	ds_read_b32 v81, v12 offset:128
	ds_read_b32 v98, v15
	ds_read_b32 v82, v14 offset:128
	ds_read_b32 v99, v17
	ds_read_b32 v83, v16 offset:128
	v_add_u32_e32 v10, 0x84, v0
	v_max_i32_e32 v11, 0, v10
	v_max_i32_e32 v10, 0xffffffe0, v10
	v_add_u32_e32 v12, 0x85, v0
	v_add_u32_e32 v14, 0x86, v0
	v_add_u32_e32 v16, 0x87, v0
	v_lshl_add_u32 v11, v11, 2, s61
	v_lshl_add_u32 v10, v10, 2, s61
	v_max_i32_e32 v13, 0, v12
	v_max_i32_e32 v12, 0xffffffe0, v12
	v_max_i32_e32 v15, 0, v14
	v_max_i32_e32 v14, 0xffffffe0, v14
	v_max_i32_e32 v17, 0, v16
	v_max_i32_e32 v16, 0xffffffe0, v16
	v_lshl_add_u32 v13, v13, 2, s61
	v_lshl_add_u32 v12, v12, 2, s61
	v_lshl_add_u32 v15, v15, 2, s61
	v_lshl_add_u32 v14, v14, 2, s61
	v_lshl_add_u32 v17, v17, 2, s61
	v_lshl_add_u32 v16, v16, 2, s61
	ds_read_b32 v100, v11
	ds_read_b32 v84, v10 offset:128
	ds_read_b32 v101, v13
	ds_read_b32 v85, v12 offset:128
	ds_read_b32 v102, v15
	ds_read_b32 v86, v14 offset:128
	ds_read_b32 v103, v17
	ds_read_b32 v87, v16 offset:128
	v_add_u32_e32 v10, 0x90, v0
	v_max_i32_e32 v11, 0, v10
	v_max_i32_e32 v10, 0xffffffe0, v10
	v_add_u32_e32 v12, 0x91, v0
	v_add_u32_e32 v14, 0x92, v0
	v_add_u32_e32 v16, 0x93, v0
	v_lshl_add_u32 v11, v11, 2, s61
	v_lshl_add_u32 v10, v10, 2, s61
	v_max_i32_e32 v13, 0, v12
	v_max_i32_e32 v12, 0xffffffe0, v12
	v_max_i32_e32 v15, 0, v14
	v_max_i32_e32 v14, 0xffffffe0, v14
	v_max_i32_e32 v17, 0, v16
	v_max_i32_e32 v16, 0xffffffe0, v16
	v_lshl_add_u32 v13, v13, 2, s61
	v_lshl_add_u32 v12, v12, 2, s61
	v_lshl_add_u32 v15, v15, 2, s61
	v_lshl_add_u32 v14, v14, 2, s61
	v_lshl_add_u32 v17, v17, 2, s61
	v_lshl_add_u32 v16, v16, 2, s61
	ds_read_b32 v104, v11
	ds_read_b32 v88, v10 offset:128
	ds_read_b32 v105, v13
	ds_read_b32 v89, v12 offset:128
	ds_read_b32 v106, v15
	ds_read_b32 v90, v14 offset:128
	ds_read_b32 v107, v17
	ds_read_b32 v91, v16 offset:128
	v_add_u32_e32 v10, 0x94, v0
	v_max_i32_e32 v11, 0, v10
	v_add_u32_e32 v12, 0x95, v0
	v_add_u32_e32 v14, 0x96, v0
	v_add_u32_e32 v0, 0x97, v0
	v_lshl_add_u32 v11, v11, 2, s61
	v_max_i32_e32 v13, 0, v12
	v_max_i32_e32 v15, 0, v14
	v_max_i32_e32 v16, 0, v0
	v_lshl_add_u32 v13, v13, 2, s61
	v_lshl_add_u32 v15, v15, 2, s61
	v_lshl_add_u32 v16, v16, 2, s61
	ds_read_b32 v108, v11
	ds_read_b32 v109, v13
	ds_read_b32 v110, v15
	ds_read_b32 v111, v16
	v_max_i32_e32 v10, 0xffffffe0, v10
	v_max_i32_e32 v12, 0xffffffe0, v12
	v_lshl_add_u32 v10, v10, 2, s61
	v_lshl_add_u32 v12, v12, 2, s61
	v_max_i32_e32 v14, 0xffffffe0, v14
	v_max_i32_e32 v0, 0xffffffe0, v0
	v_add_u32_e32 v229, 0, v200
	v_lshl_add_u32 v11, v14, 2, s61
	v_lshl_add_u32 v0, v0, 2, s61
	ds_read_b32 v92, v10 offset:128
	s_waitcnt lgkmcnt(1)
; template <bool NEAR>
; DI void attn_qk(f32x16& s0, f32x16& s1, ldsp_t kb, const int* kro, const bf16x8* qf, int dtile, const float* tb2, int hi, int qg, int r32) {
;     ...
;     for (int ks = 0; ks < 4; ++ks) { a[2 * ks] = *(const __attribute__((address_space(3))) bf16x8*)(kb + kro[ks]); a[2 * ks + 1] = *(const __attribute__((address_space(3))) bf16x8*)(kb + kro[ks] + 8192); }
;     if (!NEAR) {
;         const float c0 = tb2[0];
; #pragma unroll
;         for (int k = 0; k < 16; ++k) { s0[k] = c0; s1[k] = c0; }
;     } else {
;         const int base = dtile * 64 + 8 * hi - (qg & 1) * 32 - r32 + 128;
; #pragma unroll
;         for (int k = 0; k < 16; ++k) { const int i0 = base + (k & 7) + 16 * (k >> 3), i1 = i0 + 32; s0[k] = tb2[i0 < 0 ? 0 : i0]; s1[k] = tb2[i1 < 0 ? 0 : i1]; }
;     }
; #pragma unroll
;     for (int ks = 0; ks < 4; ++ks) { s0 = MFMA32(a[2 * ks], qf[ks], s0); s1 = MFMA32(a[2 * ks + 1], qf[ks], s1); }
; }
; DI void attn_pv(f32x16& s0, f32x16& s1, ldsp_t vb, const int* vro, f32x16* o, float& lsum) {
; #pragma unroll
;     for (int k = 0; k < 16; ++k) { s0[k] = __builtin_amdgcn_exp2f(s0[k]); s1[k] = __builtin_amdgcn_exp2f(s1[k]); }
;     float ps = 0.f;
; #pragma unroll
;     for (int k = 0; k < 16; ++k) ps += s0[k] + s1[k];
;     lsum += ps;
;     bf16x8 pk[4]; pk[0] = pack8(s0, 0); pk[1] = pack8(s0, 1); pk[2] = pack8(s1, 0); pk[3] = pack8(s1, 1);
; DI void attn_mfma_phase(PP P, int l, unsigned char* lds, int G, int cid) {
;     ...
;         f32x16 o[4];
; #pragma unroll
;         for (int et = 0; et < 4; ++et)
; #pragma unroll
;             for (int k = 0; k < 16; ++k) o[et][k] = 0.f;
;         float lsum = 0.f;
;         const bf16_t* kg[2]; const bf16_t* vg[2];
; #pragma unroll
;         for (int i2 = 0; i2 < 2; ++i2) { const int blk = wave * 2 + i2;
;             { const int row = blk * 4 + (lane >> 4), c = (lane & 15) ^ (row & 15); kg[i2] = Zk + ((size_t)b * SEQ + row) * 1024 + h * 128 + c * 8; }
;             { const int row = blk * 8 + (lane >> 3), c = (lane & 7) ^ ((row >> 1) & 7); vg[i2] = VT + ((size_t)bh * 128 + row) * SEQ + c * 8; } }
;         const int dw = wave * 2048;
;     ...
;         AT_LOADK(0); AT_LOADV(0); AT_LOADK(1);
;         __syncthreads();
;         f32x16 sc0, sc1, sn0, sn1;
;         attn_qk<true>(sc0, sc1, ldsl, kro, qf, 0 - mychunk, tb2, hi, qg, r32);
;         const int nfar = 2 * j - 3;
;         int kt = 0;
	v_mfma_f32_32x32x16_bf16 v[96:111], v[2:5], v[156:159], v[96:111]
	ds_read_b32 v93, v12 offset:128
	ds_read_b32 v94, v11 offset:128
	ds_read_b32 v95, v0 offset:128
	ds_read_b128 v[2:5], v229
	v_add_u32_e32 v230, 0, v201
	v_add_u32_e32 v231, 0, v202
	s_mov_b32 s38, 0
	s_cmp_lt_i32 s6, 2
	s_waitcnt lgkmcnt(0)
	v_mfma_f32_32x32x16_bf16 v[96:111], v[2:5], v[152:155], v[96:111]
	ds_read_b128 v[2:5], v229 offset:8192
	v_mfma_f32_32x32x16_bf16 v[80:95], v[6:9], v[156:159], v[80:95]
	s_waitcnt lgkmcnt(0)
	v_mfma_f32_32x32x16_bf16 v[80:95], v[2:5], v[152:155], v[80:95]
	ds_read_b128 v[2:5], v230
	s_waitcnt lgkmcnt(0)
	v_mfma_f32_32x32x16_bf16 v[96:111], v[2:5], v[148:151], v[96:111]
	ds_read_b128 v[2:5], v230 offset:8192
	s_waitcnt lgkmcnt(0)
	v_mfma_f32_32x32x16_bf16 v[80:95], v[2:5], v[148:151], v[80:95]
	ds_read_b128 v[2:5], v231
	s_waitcnt lgkmcnt(0)
	v_mfma_f32_32x32x16_bf16 v[96:111], v[2:5], v[144:147], v[96:111]
	ds_read_b128 v[2:5], v231 offset:8192
	s_waitcnt lgkmcnt(0)
	v_mfma_f32_32x32x16_bf16 v[80:95], v[2:5], v[144:147], v[80:95]
	s_cbranch_scc1 .LBB0_215
	s_add_u32 s6, s4, s5
	s_addc_u32 s7, 0, 0
	v_lshl_add_u64 v[10:11], v[184:185], 0, s[6:7]
	v_lshl_add_u64 v[12:13], v[186:187], 0, s[6:7]
	s_lshl_b32 s6, s42, 1
	s_andn2_b32 s6, s6, 31
	s_lshl_b32 s7, s43, 1
	s_or_b32 s6, s6, s7
	s_add_i32 s6, s6, -3
	s_max_i32 s38, s6, 1
	s_sub_i32 s7, 0, s38
	v_mov_b32_e32 v189, 0
	s_movk_i32 s6, 0x4000
	s_mov_b32 s20, 0xc0
	v_mov_b32_e32 v232, s7
	v_mov_b32_e32 v64, 0
	v_mov_b32_e32 v65, v189
	v_mov_b32_e32 v66, v189
	v_mov_b32_e32 v67, v189
	v_mov_b32_e32 v68, v189
	v_mov_b32_e32 v69, v189
	v_mov_b32_e32 v70, v189
	v_mov_b32_e32 v71, v189
	v_mov_b32_e32 v72, v189
	v_mov_b32_e32 v73, v189
	v_mov_b32_e32 v74, v189
	v_mov_b32_e32 v75, v189
	v_mov_b32_e32 v76, v189
	v_mov_b32_e32 v77, v189
	v_mov_b32_e32 v78, v189
	v_mov_b32_e32 v79, v189
	v_mov_b32_e32 v48, 0
	v_mov_b32_e32 v49, v189
	v_mov_b32_e32 v50, v189
	v_mov_b32_e32 v51, v189
	v_mov_b32_e32 v52, v189
	v_mov_b32_e32 v53, v189
	v_mov_b32_e32 v54, v189
	v_mov_b32_e32 v55, v189
	v_mov_b32_e32 v56, v189
	v_mov_b32_e32 v57, v189
	v_mov_b32_e32 v58, v189
	v_mov_b32_e32 v59, v189
	v_mov_b32_e32 v60, v189
	v_mov_b32_e32 v61, v189
	v_mov_b32_e32 v62, v189
	v_mov_b32_e32 v63, v189
	v_mov_b32_e32 v32, 0
	v_mov_b32_e32 v33, v189
	v_mov_b32_e32 v34, v189
	v_mov_b32_e32 v35, v189
	v_mov_b32_e32 v36, v189
	v_mov_b32_e32 v37, v189
	v_mov_b32_e32 v38, v189
	v_mov_b32_e32 v39, v189
	v_mov_b32_e32 v40, v189
	v_mov_b32_e32 v41, v189
	v_mov_b32_e32 v42, v189
	v_mov_b32_e32 v43, v189
	v_mov_b32_e32 v44, v189
	v_mov_b32_e32 v45, v189
	v_mov_b32_e32 v46, v189
	v_mov_b32_e32 v47, v189
	v_mov_b32_e32 v16, 0
	v_mov_b32_e32 v17, v189
	v_mov_b32_e32 v18, v189
	v_mov_b32_e32 v19, v189
	v_mov_b32_e32 v20, v189
	v_mov_b32_e32 v21, v189
	v_mov_b32_e32 v22, v189
	v_mov_b32_e32 v23, v189
	v_mov_b32_e32 v24, v189
	v_mov_b32_e32 v25, v189
	v_mov_b32_e32 v26, v189
	v_mov_b32_e32 v27, v189
	v_mov_b32_e32 v28, v189
	v_mov_b32_e32 v29, v189
	v_mov_b32_e32 v30, v189
	v_mov_b32_e32 v31, v189
	v_mov_b32_e32 v0, s61
	ds_read_b32 v112, v0
	v_exp_f32_e32 v14, v96
	v_exp_f32_e32 v15, v97
	v_exp_f32_e32 v168, v98
	v_exp_f32_e32 v169, v99
	v_exp_f32_e32 v198, v100
	v_exp_f32_e32 v199, v101
	v_exp_f32_e32 v238, v102
	v_exp_f32_e32 v239, v103
	v_cvt_pk_bf16_f32 v128, v14, v15
	v_cvt_pk_bf16_f32 v129, v168, v169
	v_add_f32_e32 v14, v14, v15
	v_add_f32_e32 v168, v168, v169
	v_cvt_pk_bf16_f32 v130, v198, v199
	v_cvt_pk_bf16_f32 v131, v238, v239
	v_add_f32_e32 v198, v198, v199
	v_add_f32_e32 v238, v238, v239
	v_add_f32_e32 v14, v14, v168
	v_add_f32_e32 v198, v198, v238
	v_add_f32_e32 v235, v14, v198
	s_waitcnt lgkmcnt(0)
	v_mov_b32_e32 v113, v112
	v_mov_b32_e32 v114, v112
	v_mov_b32_e32 v115, v112
	v_mov_b32_e32 v116, v112
	v_mov_b32_e32 v117, v112
	v_mov_b32_e32 v118, v112
	v_mov_b32_e32 v119, v112
	v_mov_b32_e32 v120, v112
	v_mov_b32_e32 v121, v112
	v_mov_b32_e32 v122, v112
	v_mov_b32_e32 v123, v112
	v_mov_b32_e32 v124, v112
	v_mov_b32_e32 v125, v112
	v_mov_b32_e32 v126, v112
	v_mov_b32_e32 v127, v112
	s_nop 0
	s_nop 0
	s_nop 0
	s_nop 0
	s_nop 0
	s_nop 0
	s_nop 0
	s_nop 0
	s_nop 0
	s_nop 0
	s_nop 0
	s_nop 0
	s_nop 0

; #define AT_LOADK(t) do { AT_DMA(kg[0] + (size_t)(t) * 65536, ldsl + ((t) & 1) * AT_KS + dw); AT_DMA(kg[1] + (size_t)(t) * 65536, ldsl + ((t) & 1) * AT_KS + dw + 1024); } while (0)
; #define AT_LOADV(t) do { AT_DMA(vg[0] + (t) * 64, ldsl + AT_V0 + ((t) & 1) * AT_KS + dw); AT_DMA(vg[1] + (t) * 64, ldsl + AT_V0 + ((t) & 1) * AT_KS + dw + 1024); } while (0)
; DI void attn_pv(f32x16& s0, f32x16& s1, ldsp_t vb, const int* vro, f32x16* o, float& lsum) {
; #pragma unroll
;     for (int k = 0; k < 16; ++k) { s0[k] = __builtin_amdgcn_exp2f(s0[k]); s1[k] = __builtin_amdgcn_exp2f(s1[k]); }
;     float ps = 0.f;
; #pragma unroll
;     for (int k = 0; k < 16; ++k) ps += s0[k] + s1[k];
;     lsum += ps;
;     bf16x8 pk[4]; pk[0] = pack8(s0, 0); pk[1] = pack8(s0, 1); pk[2] = pack8(s1, 0); pk[3] = pack8(s1, 1);
; DI void attn_mfma_phase(PP P, int l, unsigned char* lds, int G, int cid) {
;     ...
;         for (; kt < 2 * j; ++kt) {
;             AT_LOADK(kt + 2); AT_LOADV(kt + 1);
;             attn_qk<true>(sn0, sn1, ldsl + ((kt + 1) & 1) * AT_KS, kro, qf, kt + 1 - mychunk, tb2, hi, qg, r32);
;             attn_pv(sc0, sc1, ldsl + (kt & 1) * AT_KS, vro, o, lsum);
.LBB0_216:
	s_lshl_b32 s6, s43, 7
	v_subrev_u32_e32 v0, s6, v228
	s_lshl_b32 s6, s42, 7
	s_and_b32 s6, s6, 0xfffff800
	s_mov_b32 s39, s21
	s_lshl_b32 s84, s38, 6
	v_subrev_u32_e32 v232, s6, v0
	s_lshl_b32 s42, s38, 14
	s_lshl_b64 s[6:7], s[38:39], 17
	s_add_u32 s4, s4, s6
	s_addc_u32 s6, 0, s7
	s_add_u32 s4, s4, s5
	s_addc_u32 s5, s6, 0
	v_lshl_add_u64 v[10:11], v[184:185], 0, s[4:5]
	v_lshl_add_u64 v[12:13], v[186:187], 0, s[4:5]
	s_mov_b32 s4, 0xc0
	v_exp_f32_e32 v14, v96
	v_exp_f32_e32 v15, v97
	v_exp_f32_e32 v168, v98
	v_exp_f32_e32 v169, v99
	v_exp_f32_e32 v198, v100
	v_exp_f32_e32 v199, v101
	v_exp_f32_e32 v238, v102
	v_exp_f32_e32 v239, v103
	v_cvt_pk_bf16_f32 v128, v14, v15
	v_cvt_pk_bf16_f32 v129, v168, v169
	v_add_f32_e32 v14, v14, v15
	v_add_f32_e32 v168, v168, v169
	v_cvt_pk_bf16_f32 v130, v198, v199
	v_cvt_pk_bf16_f32 v131, v238, v239
	v_add_f32_e32 v198, v198, v199
	v_add_f32_e32 v238, v238, v239
	v_add_f32_e32 v14, v14, v168
	v_add_f32_e32 v198, v198, v238
	v_add_f32_e32 v235, v14, v198
	s_nop 0
	s_nop 0
	s_nop 0
	s_nop 0
	s_nop 0
